# dn_prep stage 4 tile products: all four B-operand LDS reads of a product issued together, counted waits
# baseline (speedup 1.0000x reference)
; #define LAS __attribute__((address_space(3)))
; __device__ __forceinline__ void ans_store(bf16* tile, const f32x16& v, int lane) { v4u w0, w1; ans_pack(v, w0, w1); *(v4u*)(tile + lane * 8) = w0; *(v4u*)(tile + 512 + lane * 8) = w1; }
; template <int KS> __device__ __forceinline__ void mm_lds(f32x16& acc, const LAS unsigned char* a, int aStride, const LAS unsigned char* b, int bStride, int lane) {
;     const int r = lane & 31, h = lane >> 5;
;     const LAS unsigned char* ap = a + r * aStride + h * 16; const LAS unsigned char* bp = b + r * bStride + h * 16;
; #pragma unroll
;     for (int ks = 0; ks < KS; ++ks) {
;         const bf16x8 av = *(const LAS bf16x8*)(ap + ks * 32); const bf16x8 bv = *(const LAS bf16x8*)(bp + ks * 32);
;         acc = __builtin_amdgcn_mfma_f32_32x32x16_bf16(av, bv, acc, 0, 0, 0);
;     }
; __device__ __forceinline__ void dn_prep_item(const Args& a, LAS unsigned char* lds, int item, int tid, int wave, int lane, int& cwh, int next_item) {
;     ...
;       for (int tt = 0; tt < 2; ++tt) { const int tile = 2 * wave + tt, tdp = tile >> 2, td = tile & 3;
;           f32x16 acc = zero16(); mm_lds<4>(acc, lds + L_SOL + (128 + 32 * tdp) * AS_, AS_, lds + L_KDT + 32 * td * AS_, AS_, lane);
; #pragma unroll
;           for (int r = 0; r < 16; ++r) acc[r] = -acc[r];
;           ans_store(Ms + (td * 4 + tdp) * 1024, acc, lane); }
.LBB0_881:
	s_or_b32 s42, s41, s26
	v_cndmask_b32_e64 v38, 0, 1, s[22:23]
	s_mul_i32 s22, s42, 0x1200
	v_add_u32_e32 v39, s22, v209
	ds_read_b128 v[0:3], v39
	ds_read_b128 v[34:37], v39 offset:32
	ds_read_b128 v[120:123], v39 offset:64
	ds_read_b128 v[124:127], v39 offset:96
	s_lshl_b32 s42, s42, 12
	s_add_i32 s42, s42, s27
	s_waitcnt lgkmcnt(3)
	v_mfma_f32_32x32x16_bf16 v[0:15], v[24:27], v[0:3], 0
	v_cmp_ne_u32_e32 vcc, 1, v38
	s_ashr_i32 s43, s42, 31
	s_mov_b32 s41, 1
	s_mov_b64 s[22:23], 0
	s_and_b64 vcc, exec, vcc
	s_waitcnt lgkmcnt(2)
	v_mfma_f32_32x32x16_bf16 v[0:15], v[28:31], v[34:37], v[0:15]
	s_waitcnt lgkmcnt(1)
	v_mfma_f32_32x32x16_bf16 v[0:15], v[20:23], v[120:123], v[0:15]
	v_lshl_add_u64 v[38:39], s[42:43], 1, v[32:33]
	s_waitcnt lgkmcnt(0)
	v_mfma_f32_32x32x16_bf16 v[0:15], v[16:19], v[124:127], v[0:15]
	s_nop 11
	v_xor_b32_e32 v1, 0x80000000, v1
	v_xor_b32_e32 v0, 0x80000000, v0
	v_xor_b32_e32 v2, 0x80000000, v2
	v_xor_b32_e32 v3, 0x80000000, v3
	v_xor_b32_e32 v4, 0x80000000, v4
	v_xor_b32_e32 v5, 0x80000000, v5
	v_xor_b32_e32 v6, 0x80000000, v6
	v_xor_b32_e32 v7, 0x80000000, v7
	v_xor_b32_e32 v8, 0x80000000, v8
	v_xor_b32_e32 v9, 0x80000000, v9
	v_xor_b32_e32 v10, 0x80000000, v10
	v_xor_b32_e32 v11, 0x80000000, v11
	v_xor_b32_e32 v12, 0x80000000, v12
	v_xor_b32_e32 v13, 0x80000000, v13
	v_xor_b32_e32 v14, 0x80000000, v14
	v_xor_b32_e32 v15, 0x80000000, v15
	v_cvt_pk_bf16_f32 v0, v0, v1
	v_cvt_pk_bf16_f32 v1, v2, v3
	v_cvt_pk_bf16_f32 v2, v4, v5
	v_cvt_pk_bf16_f32 v3, v6, v7
	v_cvt_pk_bf16_f32 v4, v8, v9
	v_cvt_pk_bf16_f32 v5, v10, v11
	v_cvt_pk_bf16_f32 v6, v12, v13
	v_cvt_pk_bf16_f32 v7, v14, v15
	global_store_dwordx4 v[38:39], v[0:3], off
	global_store_dwordx4 v[38:39], v[4:7], off offset:1024
	s_cbranch_vccz .LBB0_881
	ds_read_b128 v[32:35], v225
	ds_read_b128 v[36:39], v225 offset:32
	ds_read_b128 v[40:43], v225 offset:64
	ds_read_b128 v[44:47], v225 offset:96
	v_lshl_add_u64 v[72:73], s[86:87], 1, v[66:67]
	s_mov_b32 s41, 0
	s_mov_b64 s[22:23], -1
; #define LAS __attribute__((address_space(3)))
; __device__ __forceinline__ float lo_bf(unsigned w) { return __uint_as_float(w << 16); }
; template <int KS> __device__ __forceinline__ void mm_lds(f32x16& acc, const LAS unsigned char* a, int aStride, const LAS unsigned char* b, int bStride, int lane) {
;     const int r = lane & 31, h = lane >> 5;
;     const LAS unsigned char* ap = a + r * aStride + h * 16; const LAS unsigned char* bp = b + r * bStride + h * 16;
; #pragma unroll
;     for (int ks = 0; ks < KS; ++ks) {
;         const bf16x8 av = *(const LAS bf16x8*)(ap + ks * 32); const bf16x8 bv = *(const LAS bf16x8*)(bp + ks * 32);
;         acc = __builtin_amdgcn_mfma_f32_32x32x16_bf16(av, bv, acc, 0, 0, 0);
;     }
; __device__ __forceinline__ void dn_prep_item(const Args& a, LAS unsigned char* lds, int item, int tid, int wave, int lane, int& cwh, int next_item) {
;     ...
; #pragma unroll 1
;       for (int tt = 0; tt < 2; ++tt) { const int tile = 2 * wave + tt, td = tile >> 2, te = tile & 3;
;           f32x16 acc = zero16(); mm_lds<4>(acc, lds + L_KDT + 32 * td * AS_, AS_, lds + L_SOL + 32 * te * AS_, AS_, lane);
;           ans_store(Bs + (te * 4 + td) * 1024, acc, lane); }
;       { const int td = wave >> 1, ti = wave & 1;
;           f32x16 acc = zero16(); mm_lds<4>(acc, lds + L_SOL + (128 + 32 * td) * AS_, AS_, lds + L_AT + 32 * ti * AS_, AS_, lane);
;           const int i = 32 * ti + rr; const float eg = __expf(gcs[i]);
; #pragma unroll
;           for (int g = 0; g < 4; ++g) { const v2u qv = *(const LAS v2u*)(lds + L_QS + i * KS_ + 2 * (32 * td + 8 * g + 4 * hh));
;               acc[4 * g] = lo_bf(qv.x) * eg - acc[4 * g]; acc[4 * g + 1] = hi_bf(qv.x) * eg - acc[4 * g + 1]; acc[4 * g + 2] = lo_bf(qv.y) * eg - acc[4 * g + 2]; acc[4 * g + 3] = hi_bf(qv.y) * eg - acc[4 * g + 3]; }
;           ans_store(Qp + (ti * 4 + td) * 1024, acc, lane); }
;       { const int ti = wave & 1, te = wave >> 1;
;           f32x16 acc = zero16(); mm_lds<4>(acc, lds + L_AT + 32 * ti * AS_, AS_, lds + L_SOL + 32 * te * AS_, AS_, lane);
;           v4u w0, w1; ans_pack(acc, w0, w1); const int eo = (ti * 4 + te) * 1024 + lane * 8;
;           *(v4u*)yslot(Y, tok0, h, eo) = w0; *(v4u*)yslot(Y, tok0, h, eo + 512) = w1; }
;       if (tid == 0) ((float*)(ws + WS_GL))[item] = __expf(gcs[63]);
.LBB0_883:
	s_or_b32 s42, s41, s26
	v_cndmask_b32_e64 v0, 0, 1, s[22:23]
	s_lshl_b32 s22, s42, 12
	s_mulk_i32 s42, 0x1200
	v_add_u32_e32 v56, s42, v210
	v_cmp_ne_u32_e32 vcc, 1, v0
	ds_read_b128 v[0:3], v56 offset:61440
	ds_read_b128 v[74:77], v56 offset:61472
	ds_read_b128 v[120:123], v56 offset:61504
	ds_read_b128 v[124:127], v56 offset:61536
	s_waitcnt lgkmcnt(3)
	v_mfma_f32_32x32x16_bf16 v[0:15], v[32:35], v[0:3], 0
	s_add_i32 s22, s22, s27
	s_ashr_i32 s23, s22, 31
	s_mov_b32 s41, 1
	s_and_b64 vcc, exec, vcc
	s_waitcnt lgkmcnt(2)
	v_mfma_f32_32x32x16_bf16 v[0:15], v[36:39], v[74:77], v[0:15]
	s_waitcnt lgkmcnt(1)
	v_mfma_f32_32x32x16_bf16 v[0:15], v[40:43], v[120:123], v[0:15]
	s_waitcnt lgkmcnt(0)
	v_mfma_f32_32x32x16_bf16 v[0:15], v[44:47], v[124:127], v[0:15]
	s_nop 11
	v_cvt_pk_bf16_f32 v0, v0, v1
	v_cvt_pk_bf16_f32 v1, v2, v3
	v_cvt_pk_bf16_f32 v2, v4, v5
	v_cvt_pk_bf16_f32 v3, v6, v7
	v_cvt_pk_bf16_f32 v4, v8, v9
	v_lshl_add_u64 v[8:9], s[22:23], 1, v[72:73]
	s_mov_b64 s[22:23], 0
	v_cvt_pk_bf16_f32 v5, v10, v11
	v_cvt_pk_bf16_f32 v6, v12, v13
	v_cvt_pk_bf16_f32 v7, v14, v15
	global_store_dwordx4 v[8:9], v[0:3], off
	global_store_dwordx4 v[8:9], v[4:7], off offset:1024
	s_cbranch_vccz .LBB0_883
	ds_read_b128 v[32:35], v226 offset:52224
	ds_read_b128 v[36:39], v226 offset:52256
	ds_read_b128 v[120:123], v226 offset:52288
	ds_read_b128 v[124:127], v226 offset:52320
	s_lshl_b32 s22, s40, 1
	s_mov_b32 s23, s9
	v_mov_b32_e32 v71, v57
	s_waitcnt lgkmcnt(3)
	v_mfma_f32_32x32x16_bf16 v[0:15], v[24:27], v[32:35], 0
	s_waitcnt lgkmcnt(2)
	v_mfma_f32_32x32x16_bf16 v[0:15], v[28:31], v[36:39], v[0:15]
	v_add_u32_e32 v28, 0x4000, v227
	s_waitcnt lgkmcnt(1)
	v_mfma_f32_32x32x16_bf16 v[0:15], v[20:23], v[120:123], v[0:15]
	s_waitcnt lgkmcnt(0)
	v_mfma_f32_32x32x16_bf16 v[0:15], v[16:19], v[124:127], v[0:15]
	ds_read_b32 v16, v211
	s_waitcnt lgkmcnt(0)
	v_mul_f32_e32 v16, 0x3fb8aa3b, v16
	v_exp_f32_e32 v40, v16
	ds_read2_b64 v[16:19], v28 offset0:128 offset1:130
	ds_read2_b64 v[28:31], v28 offset0:132 offset1:134
	s_waitcnt lgkmcnt(1)
	v_lshlrev_b32_e32 v42, 16, v16
	v_and_b32_e32 v43, 0xffff0000, v16
	v_lshlrev_b32_e32 v16, 16, v17
	v_and_b32_e32 v17, 0xffff0000, v17
	s_nop 0
	v_pk_fma_f32 v[2:3], v[40:41], v[16:17], v[2:3] op_sel_hi:[0,1,1] neg_lo:[0,0,1] neg_hi:[0,0,1]
	v_lshlrev_b32_e32 v16, 16, v18
	v_and_b32_e32 v17, 0xffff0000, v18
	v_pk_fma_f32 v[4:5], v[40:41], v[16:17], v[4:5] op_sel_hi:[0,1,1] neg_lo:[0,0,1] neg_hi:[0,0,1]
	v_lshlrev_b32_e32 v16, 16, v19
	v_and_b32_e32 v17, 0xffff0000, v19
	v_pk_fma_f32 v[6:7], v[40:41], v[16:17], v[6:7] op_sel_hi:[0,1,1] neg_lo:[0,0,1] neg_hi:[0,0,1]
	s_waitcnt lgkmcnt(0)
	v_lshlrev_b32_e32 v16, 16, v28
	v_and_b32_e32 v17, 0xffff0000, v28
	v_pk_fma_f32 v[8:9], v[40:41], v[16:17], v[8:9] op_sel_hi:[0,1,1] neg_lo:[0,0,1] neg_hi:[0,0,1]
	v_lshlrev_b32_e32 v16, 16, v29
	v_and_b32_e32 v17, 0xffff0000, v29
	v_pk_fma_f32 v[10:11], v[40:41], v[16:17], v[10:11] op_sel_hi:[0,1,1] neg_lo:[0,0,1] neg_hi:[0,0,1]
	v_lshlrev_b32_e32 v16, 16, v30
	v_and_b32_e32 v17, 0xffff0000, v30
	v_pk_fma_f32 v[0:1], v[40:41], v[42:43], v[0:1] op_sel_hi:[0,1,1] neg_lo:[0,0,1] neg_hi:[0,0,1]
	v_pk_fma_f32 v[12:13], v[40:41], v[16:17], v[12:13] op_sel_hi:[0,1,1] neg_lo:[0,0,1] neg_hi:[0,0,1]
	v_lshlrev_b32_e32 v16, 16, v31
	v_and_b32_e32 v17, 0xffff0000, v31
	v_pk_fma_f32 v[14:15], v[40:41], v[16:17], v[14:15] op_sel_hi:[0,1,1] neg_lo:[0,0,1] neg_hi:[0,0,1]
	v_cvt_pk_bf16_f32 v0, v0, v1
	v_cvt_pk_bf16_f32 v1, v2, v3
	v_cvt_pk_bf16_f32 v2, v4, v5
	v_cvt_pk_bf16_f32 v3, v6, v7
	v_cvt_pk_bf16_f32 v4, v8, v9
	v_lshl_add_u64 v[8:9], v[68:69], 0, s[86:87]
	v_cvt_pk_bf16_f32 v5, v10, v11
	v_cvt_pk_bf16_f32 v6, v12, v13
	v_cvt_pk_bf16_f32 v7, v14, v15
	global_store_dwordx4 v[8:9], v[0:3], off
	global_store_dwordx4 v[8:9], v[4:7], off offset:1024
	ds_read_b128 v[0:3], v228 offset:61440
	ds_read_b128 v[16:19], v228 offset:61472
	ds_read_b128 v[128:131], v228 offset:61504
	ds_read_b128 v[132:135], v228 offset:61536
	s_waitcnt lgkmcnt(3)
	v_mfma_f32_32x32x16_bf16 v[0:15], v[32:35], v[0:3], 0
	s_waitcnt lgkmcnt(2)
	v_mfma_f32_32x32x16_bf16 v[0:15], v[36:39], v[16:19], v[0:15]
	s_waitcnt lgkmcnt(1)
	v_mfma_f32_32x32x16_bf16 v[0:15], v[120:123], v[128:131], v[0:15]
	s_waitcnt lgkmcnt(0)
	v_mfma_f32_32x32x16_bf16 v[0:15], v[124:127], v[132:135], v[0:15]
	s_nop 11
	v_cvt_pk_bf16_f32 v0, v0, v1
	v_cvt_pk_bf16_f32 v1, v2, v3
	v_cvt_pk_bf16_f32 v2, v4, v5
	v_cvt_pk_bf16_f32 v4, v8, v9
	v_add_u32_e32 v8, s39, v212
	v_ashrrev_i32_e32 v9, 31, v8
	v_lshlrev_b64 v[8:9], 11, v[8:9]
	v_lshl_add_u64 v[8:9], s[12:13], 0, v[8:9]
	v_lshl_add_u64 v[8:9], v[8:9], 0, s[22:23]
	v_cvt_pk_bf16_f32 v3, v6, v7
	v_lshl_add_u64 v[8:9], v[8:9], 0, v[70:71]
	global_store_dwordx4 v[8:9], v[0:3], off offset:1024
	v_cvt_pk_bf16_f32 v5, v10, v11
	v_cvt_pk_bf16_f32 v6, v12, v13
	v_add_u32_e32 v0, s39, v213
	v_ashrrev_i32_e32 v1, 31, v0
	v_lshlrev_b64 v[0:1], 11, v[0:1]
	v_lshl_add_u64 v[0:1], s[12:13], 0, v[0:1]
	v_lshl_add_u64 v[0:1], v[0:1], 0, s[22:23]
	v_cvt_pk_bf16_f32 v7, v14, v15
	v_lshl_add_u64 v[0:1], v[0:1], 0, v[70:71]
	global_store_dwordx4 v[0:1], v[4:7], off offset:1024
	s_and_saveexec_b64 s[22:23], s[88:89]
	s_cbranch_execz .LBB0_735
	v_mov_b32_e32 v0, s35
	ds_read_b32 v0, v0
	s_lshl_b64 s[40:41], s[8:9], 2
	s_add_u32 s40, s28, s40
	s_addc_u32 s41, s29, s41
	s_waitcnt lgkmcnt(0)
	v_mul_f32_e32 v0, 0x3fb8aa3b, v0
	v_exp_f32_e32 v0, v0
	global_store_dword v57, v0, s[40:41]
	s_branch .LBB0_735
